# scan_unit: the 32 wave-uniform decay-scalar loads of a batch replaced by one lane-strided load + v_readlane broadcasts
# speedup vs baseline: 1.0088x; 1.0052x over previous
.LBB0_670:
	v_and_b32_e32 v101, 31, v193
	v_lshlrev_b32_e32 v101, 6, v101
	s_lshl_b32 s8, s12, 18
	v_lshl_add_u64 v[10:11], v[6:7], 0, s[8:9]
	s_lshl_b32 s8, s12, 4
	s_lshl_b64 s[14:15], s[8:9], 2
	s_add_u32 s14, s23, s14
	s_addc_u32 s15, s24, s15
	s_or_b32 s13, s12, 1
	s_lshl_b32 s8, s13, 18
	v_lshl_add_u64 v[12:13], v[6:7], 0, s[8:9]
	s_lshl_b32 s8, s13, 4
	global_load_dword v73, v[10:11], off
	global_load_dword v100, v101, s[14:15]
	s_lshl_b64 s[14:15], s[8:9], 2
	s_add_u32 s14, s23, s14
	s_addc_u32 s15, s24, s15
	s_or_b32 s13, s12, 2
	s_lshl_b32 s8, s13, 18
	global_load_dword v71, v[12:13], off
	v_lshl_add_u64 v[12:13], v[6:7], 0, s[8:9]
	s_lshl_b32 s8, s13, 4
	s_lshl_b64 s[14:15], s[8:9], 2
	s_add_u32 s14, s23, s14
	s_addc_u32 s15, s24, s15
	s_or_b32 s13, s12, 3
	s_lshl_b32 s8, s13, 18
	global_load_dword v69, v[12:13], off
	v_lshl_add_u64 v[12:13], v[6:7], 0, s[8:9]
	s_lshl_b32 s8, s13, 4
	s_lshl_b64 s[14:15], s[8:9], 2
	s_add_u32 s14, s23, s14
	s_addc_u32 s15, s24, s15
	s_or_b32 s13, s12, 4
	s_lshl_b32 s8, s13, 18
	global_load_dword v67, v[12:13], off
	v_lshl_add_u64 v[12:13], v[6:7], 0, s[8:9]
	s_lshl_b32 s8, s13, 4
	s_lshl_b64 s[14:15], s[8:9], 2
	s_add_u32 s14, s23, s14
	s_addc_u32 s15, s24, s15
	s_or_b32 s13, s12, 5
	s_lshl_b32 s8, s13, 18
	global_load_dword v65, v[12:13], off
	v_lshl_add_u64 v[12:13], v[6:7], 0, s[8:9]
	s_lshl_b32 s8, s13, 4
	s_lshl_b64 s[14:15], s[8:9], 2
	s_add_u32 s14, s23, s14
	s_addc_u32 s15, s24, s15
	s_or_b32 s13, s12, 6
	s_lshl_b32 s8, s13, 18
	global_load_dword v63, v[12:13], off
	v_lshl_add_u64 v[12:13], v[6:7], 0, s[8:9]
	s_lshl_b32 s8, s13, 4
	s_lshl_b64 s[14:15], s[8:9], 2
	s_add_u32 s14, s23, s14
	s_addc_u32 s15, s24, s15
	s_or_b32 s13, s12, 7
	s_lshl_b32 s8, s13, 18
	global_load_dword v61, v[12:13], off
	v_lshl_add_u64 v[12:13], v[6:7], 0, s[8:9]
	s_lshl_b32 s8, s13, 4
	s_lshl_b64 s[14:15], s[8:9], 2
	s_add_u32 s14, s23, s14
	s_addc_u32 s15, s24, s15
	s_or_b32 s13, s12, 8
	s_lshl_b32 s8, s13, 18
	global_load_dword v59, v[12:13], off
	v_lshl_add_u64 v[12:13], v[6:7], 0, s[8:9]
	s_lshl_b32 s8, s13, 4
	s_lshl_b64 s[14:15], s[8:9], 2
	s_add_u32 s14, s23, s14
	s_addc_u32 s15, s24, s15
	s_or_b32 s13, s12, 9
	s_lshl_b32 s8, s13, 18
	global_load_dword v57, v[12:13], off
	v_lshl_add_u64 v[12:13], v[6:7], 0, s[8:9]
	s_lshl_b32 s8, s13, 4
	s_lshl_b64 s[14:15], s[8:9], 2
	s_add_u32 s14, s23, s14
	s_addc_u32 s15, s24, s15
	s_or_b32 s13, s12, 10
	s_lshl_b32 s8, s13, 18
	global_load_dword v55, v[12:13], off
	v_lshl_add_u64 v[12:13], v[6:7], 0, s[8:9]
	s_lshl_b32 s8, s13, 4
	s_lshl_b64 s[14:15], s[8:9], 2
	s_add_u32 s14, s23, s14
	s_addc_u32 s15, s24, s15
	s_or_b32 s13, s12, 11
	s_lshl_b32 s8, s13, 18
	global_load_dword v53, v[12:13], off
	v_lshl_add_u64 v[12:13], v[6:7], 0, s[8:9]
	s_lshl_b32 s8, s13, 4
	s_lshl_b64 s[14:15], s[8:9], 2
	s_add_u32 s14, s23, s14
	s_addc_u32 s15, s24, s15
	s_or_b32 s13, s12, 12
	s_lshl_b32 s8, s13, 18
	global_load_dword v51, v[12:13], off
	v_lshl_add_u64 v[12:13], v[6:7], 0, s[8:9]
	s_lshl_b32 s8, s13, 4
	s_lshl_b64 s[14:15], s[8:9], 2
	s_add_u32 s14, s23, s14
	s_addc_u32 s15, s24, s15
	s_or_b32 s13, s12, 13
	s_lshl_b32 s8, s13, 18
	global_load_dword v49, v[12:13], off
	v_lshl_add_u64 v[12:13], v[6:7], 0, s[8:9]
	s_lshl_b32 s8, s13, 4
	s_lshl_b64 s[14:15], s[8:9], 2
	s_add_u32 s14, s23, s14
	s_addc_u32 s15, s24, s15
	s_or_b32 s13, s12, 14
	s_lshl_b32 s8, s13, 18
	global_load_dword v47, v[12:13], off
	v_lshl_add_u64 v[12:13], v[6:7], 0, s[8:9]
	s_lshl_b32 s8, s13, 4
	s_lshl_b64 s[14:15], s[8:9], 2
	s_add_u32 s14, s23, s14
	s_addc_u32 s15, s24, s15
	s_or_b32 s13, s12, 15
	s_lshl_b32 s8, s13, 18
	global_load_dword v45, v[12:13], off
	v_lshl_add_u64 v[12:13], v[6:7], 0, s[8:9]
	s_lshl_b32 s8, s13, 4
	s_lshl_b64 s[14:15], s[8:9], 2
	s_add_u32 s14, s23, s14
	s_addc_u32 s15, s24, s15
	s_or_b32 s13, s12, 16
	s_lshl_b32 s8, s13, 18
	global_load_dword v41, v[12:13], off
	v_lshl_add_u64 v[12:13], v[6:7], 0, s[8:9]
	s_lshl_b32 s8, s13, 4
	s_lshl_b64 s[14:15], s[8:9], 2
	s_add_u32 s14, s23, s14
	s_addc_u32 s15, s24, s15
	s_or_b32 s13, s12, 17
	s_lshl_b32 s8, s13, 18
	global_load_dword v39, v[12:13], off
	v_lshl_add_u64 v[12:13], v[6:7], 0, s[8:9]
	s_lshl_b32 s8, s13, 4
	s_lshl_b64 s[14:15], s[8:9], 2
	s_add_u32 s14, s23, s14
	s_addc_u32 s15, s24, s15
	s_or_b32 s13, s12, 18
	s_lshl_b32 s8, s13, 18
	global_load_dword v37, v[12:13], off
	v_lshl_add_u64 v[12:13], v[6:7], 0, s[8:9]
	s_lshl_b32 s8, s13, 4
	s_lshl_b64 s[14:15], s[8:9], 2
	s_add_u32 s14, s23, s14
	s_addc_u32 s15, s24, s15
	s_or_b32 s13, s12, 19
	s_lshl_b32 s8, s13, 18
	global_load_dword v35, v[12:13], off
	v_lshl_add_u64 v[12:13], v[6:7], 0, s[8:9]
	s_lshl_b32 s8, s13, 4
	s_lshl_b64 s[14:15], s[8:9], 2
	s_add_u32 s14, s23, s14
	s_addc_u32 s15, s24, s15
	s_or_b32 s13, s12, 20
	s_lshl_b32 s8, s13, 18
	global_load_dword v29, v[12:13], off
	v_lshl_add_u64 v[12:13], v[6:7], 0, s[8:9]
	s_lshl_b32 s8, s13, 4
	s_lshl_b64 s[14:15], s[8:9], 2
	s_add_u32 s14, s23, s14
	s_addc_u32 s15, s24, s15
	s_or_b32 s13, s12, 21
	s_lshl_b32 s8, s13, 18
	global_load_dword v19, v[12:13], off
	v_lshl_add_u64 v[12:13], v[6:7], 0, s[8:9]
	s_lshl_b32 s8, s13, 4
	s_lshl_b64 s[14:15], s[8:9], 2
	s_add_u32 s14, s23, s14
	s_addc_u32 s15, s24, s15
	s_or_b32 s13, s12, 22
	s_lshl_b32 s8, s13, 18
	global_load_dword v5, v[12:13], off
	v_lshl_add_u64 v[12:13], v[6:7], 0, s[8:9]
	s_lshl_b32 s8, s13, 4
	s_lshl_b64 s[14:15], s[8:9], 2
	s_add_u32 s14, s23, s14
	s_addc_u32 s15, s24, s15
	s_or_b32 s13, s12, 23
	s_lshl_b32 s8, s13, 18
	v_lshl_add_u64 v[14:15], v[6:7], 0, s[8:9]
	s_lshl_b32 s8, s13, 4
	global_load_dword v13, v[12:13], off
	v_cvt_pk_bf16_f32 v75, v8, v9
	s_lshl_b64 s[14:15], s[8:9], 2
	s_add_u32 s14, s23, s14
	s_addc_u32 s15, s24, s15
	s_or_b32 s13, s12, 24
	s_lshl_b32 s8, s13, 18
	v_lshl_add_u64 v[16:17], v[6:7], 0, s[8:9]
	s_lshl_b32 s8, s13, 4
	global_load_dword v15, v[14:15], off
	s_nop 0
	s_lshl_b64 s[14:15], s[8:9], 2
	s_add_u32 s14, s23, s14
	s_addc_u32 s15, s24, s15
	s_or_b32 s13, s12, 25
	s_lshl_b32 s8, s13, 18
	v_lshl_add_u64 v[20:21], v[6:7], 0, s[8:9]
	s_lshl_b32 s8, s13, 4
	global_load_dword v17, v[16:17], off
	s_nop 0
	s_lshl_b64 s[14:15], s[8:9], 2
	s_add_u32 s14, s23, s14
	s_addc_u32 s15, s24, s15
	s_or_b32 s13, s12, 26
	s_lshl_b32 s8, s13, 18
	v_lshl_add_u64 v[22:23], v[6:7], 0, s[8:9]
	s_lshl_b32 s8, s13, 4
	global_load_dword v21, v[20:21], off
	s_nop 0
	global_load_dword v23, v[22:23], off
	s_nop 0
	s_lshl_b64 s[14:15], s[8:9], 2
	s_add_u32 s14, s23, s14
	s_addc_u32 s15, s24, s15
	s_or_b32 s13, s12, 27
	s_lshl_b32 s8, s13, 18
	v_lshl_add_u64 v[76:77], v[6:7], 0, s[8:9]
	s_lshl_b32 s8, s13, 4
	global_load_dword v25, v[76:77], off
	s_lshl_b64 s[14:15], s[8:9], 2
	s_add_u32 s14, s23, s14
	s_addc_u32 s15, s24, s15
	s_or_b32 s13, s12, 28
	s_lshl_b32 s8, s13, 18
	v_lshl_add_u64 v[76:77], v[6:7], 0, s[8:9]
	s_lshl_b32 s8, s13, 4
	global_load_dword v27, v[76:77], off
	s_lshl_b64 s[14:15], s[8:9], 2
	s_add_u32 s14, s23, s14
	s_addc_u32 s15, s24, s15
	s_or_b32 s13, s12, 29
	s_lshl_b32 s8, s13, 18
	v_lshl_add_u64 v[76:77], v[6:7], 0, s[8:9]
	s_lshl_b32 s8, s13, 4
	global_load_dword v31, v[76:77], off
	s_lshl_b64 s[14:15], s[8:9], 2
	s_add_u32 s14, s23, s14
	s_addc_u32 s15, s24, s15
	s_or_b32 s13, s12, 30
	s_lshl_b32 s8, s13, 18
	v_lshl_add_u64 v[76:77], v[6:7], 0, s[8:9]
	s_lshl_b32 s8, s13, 4
	global_load_dword v33, v[76:77], off
	s_lshl_b64 s[14:15], s[8:9], 2
	s_add_u32 s14, s23, s14
	s_addc_u32 s15, s24, s15
	s_or_b32 s12, s12, 31
	s_lshl_b32 s8, s12, 18
	v_lshl_add_u64 v[76:77], v[6:7], 0, s[8:9]
	global_load_dword v43, v[76:77], off
	s_lshl_b32 s8, s12, 4
	s_lshl_b64 s[12:13], s[8:9], 2
	s_waitcnt vmcnt(0)
	v_readlane_b32 s100, v100, 0
	v_readlane_b32 s101, v100, 1
	s_nop 0
	v_mov_b32_e32 v74, s100
	v_mov_b32_e32 v72, s101
	v_readlane_b32 s100, v100, 2
	v_readlane_b32 s101, v100, 3
	s_nop 0
	v_mov_b32_e32 v70, s100
	v_mov_b32_e32 v68, s101
	v_readlane_b32 s100, v100, 4
	v_readlane_b32 s101, v100, 5
	s_nop 0
	v_mov_b32_e32 v66, s100
	v_mov_b32_e32 v64, s101
	v_readlane_b32 s100, v100, 6
	v_readlane_b32 s101, v100, 7
	s_nop 0
	v_mov_b32_e32 v62, s100
	v_mov_b32_e32 v60, s101
	v_readlane_b32 s100, v100, 8
	v_readlane_b32 s101, v100, 9
	s_nop 0
	v_mov_b32_e32 v58, s100
	v_mov_b32_e32 v56, s101
	v_readlane_b32 s100, v100, 10
	v_readlane_b32 s101, v100, 11
	s_nop 0
	v_mov_b32_e32 v54, s100
	v_mov_b32_e32 v52, s101
	v_readlane_b32 s100, v100, 12
	v_readlane_b32 s101, v100, 13
	s_nop 0
	v_mov_b32_e32 v50, s100
	v_mov_b32_e32 v48, s101
	v_readlane_b32 s100, v100, 14
	v_readlane_b32 s101, v100, 15
	s_nop 0
	v_mov_b32_e32 v46, s100
	v_mov_b32_e32 v44, s101
	v_readlane_b32 s100, v100, 16
	v_readlane_b32 s101, v100, 17
	s_nop 0
	v_mov_b32_e32 v42, s100
	v_mov_b32_e32 v40, s101
	v_readlane_b32 s100, v100, 18
	v_readlane_b32 s101, v100, 19
	s_nop 0
	v_mov_b32_e32 v38, s100
	v_mov_b32_e32 v36, s101
	v_readlane_b32 s100, v100, 20
	v_readlane_b32 s101, v100, 21
	s_nop 0
	v_mov_b32_e32 v34, s100
	v_mov_b32_e32 v32, s101
	v_readlane_b32 s100, v100, 22
	v_readlane_b32 s101, v100, 23
	s_nop 0
	v_mov_b32_e32 v30, s100
	v_mov_b32_e32 v28, s101
	v_readlane_b32 s100, v100, 24
	v_readlane_b32 s101, v100, 25
	s_nop 0
	v_mov_b32_e32 v26, s100
	v_mov_b32_e32 v24, s101
	v_readlane_b32 s100, v100, 26
	v_readlane_b32 s101, v100, 27
	s_nop 0
	v_mov_b32_e32 v22, s100
	v_mov_b32_e32 v20, s101
	v_readlane_b32 s100, v100, 28
	v_readlane_b32 s101, v100, 29
	s_nop 0
	v_mov_b32_e32 v18, s100
	v_mov_b32_e32 v16, s101
	v_readlane_b32 s100, v100, 30
	s_nop 1
	v_mov_b32_e32 v14, s100
	v_lshlrev_b32_e32 v76, 16, v73
	v_and_b32_e32 v77, 0xffff0000, v73
	s_mov_b32 s8, 0x40000
	s_add_u32 s12, s23, s12
	v_pk_fma_f32 v[8:9], v[8:9], v[74:75], v[76:77] op_sel_hi:[1,0,1]
	v_add_co_u32_e32 v74, vcc, s8, v10
	s_addc_u32 s13, s24, s13
	global_store_dword v[10:11], v75, off
	v_cvt_pk_bf16_f32 v73, v8, v9
	v_addc_co_u32_e32 v75, vcc, 0, v11, vcc
	v_readlane_b32 s100, v100, 31
	s_nop 1
	v_mov_b32_e32 v12, s100
	s_mov_b32 s8, 0x80000
	global_store_dword v[74:75], v73, off
	v_lshlrev_b32_e32 v74, 16, v71
	v_and_b32_e32 v75, 0xffff0000, v71
	v_pk_fma_f32 v[8:9], v[8:9], v[72:73], v[74:75] op_sel_hi:[1,0,1]
	v_add_co_u32_e32 v72, vcc, s8, v10
	v_cvt_pk_bf16_f32 v71, v8, v9
	s_nop 0
	v_addc_co_u32_e32 v73, vcc, 0, v11, vcc
	global_store_dword v[72:73], v71, off
	v_lshlrev_b32_e32 v72, 16, v69
	v_and_b32_e32 v73, 0xffff0000, v69
	s_mov_b32 s8, 0xc0000
	v_pk_fma_f32 v[8:9], v[8:9], v[70:71], v[72:73] op_sel_hi:[1,0,1]
	v_add_co_u32_e32 v70, vcc, s8, v10
	v_cvt_pk_bf16_f32 v69, v8, v9
	s_nop 0
	v_addc_co_u32_e32 v71, vcc, 0, v11, vcc
	global_store_dword v[70:71], v69, off
	v_lshlrev_b32_e32 v70, 16, v67
	v_and_b32_e32 v71, 0xffff0000, v67
	s_mov_b32 s8, 0x100000
	v_pk_fma_f32 v[8:9], v[8:9], v[68:69], v[70:71] op_sel_hi:[1,0,1]
	v_add_co_u32_e32 v68, vcc, s8, v10
	v_cvt_pk_bf16_f32 v67, v8, v9
	s_nop 0
	v_addc_co_u32_e32 v69, vcc, 0, v11, vcc
	global_store_dword v[68:69], v67, off
	v_lshlrev_b32_e32 v68, 16, v65
	v_and_b32_e32 v69, 0xffff0000, v65
	s_mov_b32 s8, 0x140000
	v_pk_fma_f32 v[8:9], v[8:9], v[66:67], v[68:69] op_sel_hi:[1,0,1]
	v_add_co_u32_e32 v66, vcc, s8, v10
	v_cvt_pk_bf16_f32 v65, v8, v9
	s_nop 0
	v_addc_co_u32_e32 v67, vcc, 0, v11, vcc
	global_store_dword v[66:67], v65, off
	v_lshlrev_b32_e32 v66, 16, v63
	v_and_b32_e32 v67, 0xffff0000, v63
	s_mov_b32 s8, 0x180000
	v_pk_fma_f32 v[8:9], v[8:9], v[64:65], v[66:67] op_sel_hi:[1,0,1]
	v_add_co_u32_e32 v64, vcc, s8, v10
	v_cvt_pk_bf16_f32 v63, v8, v9
	s_nop 0
	v_addc_co_u32_e32 v65, vcc, 0, v11, vcc
	global_store_dword v[64:65], v63, off
	v_lshlrev_b32_e32 v64, 16, v61
	v_and_b32_e32 v65, 0xffff0000, v61
	s_mov_b32 s8, 0x1c0000
	v_pk_fma_f32 v[8:9], v[8:9], v[62:63], v[64:65] op_sel_hi:[1,0,1]
	v_add_co_u32_e32 v62, vcc, s8, v10
	v_cvt_pk_bf16_f32 v61, v8, v9
	s_nop 0
	v_addc_co_u32_e32 v63, vcc, 0, v11, vcc
	global_store_dword v[62:63], v61, off
	v_lshlrev_b32_e32 v62, 16, v59
	v_and_b32_e32 v63, 0xffff0000, v59
	s_mov_b32 s8, 0x200000
	v_pk_fma_f32 v[8:9], v[8:9], v[60:61], v[62:63] op_sel_hi:[1,0,1]
	v_add_co_u32_e32 v60, vcc, s8, v10
	v_cvt_pk_bf16_f32 v59, v8, v9
	s_nop 0
	v_addc_co_u32_e32 v61, vcc, 0, v11, vcc
	global_store_dword v[60:61], v59, off
	v_lshlrev_b32_e32 v60, 16, v57
	v_and_b32_e32 v61, 0xffff0000, v57
	s_mov_b32 s8, 0x240000
	v_pk_fma_f32 v[8:9], v[8:9], v[58:59], v[60:61] op_sel_hi:[1,0,1]
	v_add_co_u32_e32 v58, vcc, s8, v10
	v_cvt_pk_bf16_f32 v57, v8, v9
	s_nop 0
	v_addc_co_u32_e32 v59, vcc, 0, v11, vcc
	global_store_dword v[58:59], v57, off
	v_lshlrev_b32_e32 v58, 16, v55
	v_and_b32_e32 v59, 0xffff0000, v55
	s_mov_b32 s8, 0x280000
	v_pk_fma_f32 v[8:9], v[8:9], v[56:57], v[58:59] op_sel_hi:[1,0,1]
	v_add_co_u32_e32 v56, vcc, s8, v10
	v_cvt_pk_bf16_f32 v55, v8, v9
	s_nop 0
	v_addc_co_u32_e32 v57, vcc, 0, v11, vcc
	global_store_dword v[56:57], v55, off
	v_lshlrev_b32_e32 v56, 16, v53
	v_and_b32_e32 v57, 0xffff0000, v53
	s_mov_b32 s8, 0x2c0000
	v_pk_fma_f32 v[8:9], v[8:9], v[54:55], v[56:57] op_sel_hi:[1,0,1]
	v_add_co_u32_e32 v54, vcc, s8, v10
	v_cvt_pk_bf16_f32 v53, v8, v9
	s_nop 0
	v_addc_co_u32_e32 v55, vcc, 0, v11, vcc
	global_store_dword v[54:55], v53, off
	v_lshlrev_b32_e32 v54, 16, v51
	v_and_b32_e32 v55, 0xffff0000, v51
	s_mov_b32 s8, 0x300000
	v_pk_fma_f32 v[8:9], v[8:9], v[52:53], v[54:55] op_sel_hi:[1,0,1]
	v_add_co_u32_e32 v52, vcc, s8, v10
	v_cvt_pk_bf16_f32 v51, v8, v9
	s_nop 0
	v_addc_co_u32_e32 v53, vcc, 0, v11, vcc
	global_store_dword v[52:53], v51, off
	v_lshlrev_b32_e32 v52, 16, v49
	v_and_b32_e32 v53, 0xffff0000, v49
	s_mov_b32 s8, 0x340000
	v_pk_fma_f32 v[8:9], v[8:9], v[50:51], v[52:53] op_sel_hi:[1,0,1]
	v_add_co_u32_e32 v50, vcc, s8, v10
	v_cvt_pk_bf16_f32 v49, v8, v9
	s_nop 0
	v_addc_co_u32_e32 v51, vcc, 0, v11, vcc
	global_store_dword v[50:51], v49, off
	v_lshlrev_b32_e32 v50, 16, v47
	v_and_b32_e32 v51, 0xffff0000, v47
	s_mov_b32 s8, 0x380000
	v_pk_fma_f32 v[8:9], v[8:9], v[48:49], v[50:51] op_sel_hi:[1,0,1]
	v_add_co_u32_e32 v48, vcc, s8, v10
	v_cvt_pk_bf16_f32 v47, v8, v9
	s_nop 0
	v_addc_co_u32_e32 v49, vcc, 0, v11, vcc
	global_store_dword v[48:49], v47, off
	v_lshlrev_b32_e32 v48, 16, v45
	v_and_b32_e32 v49, 0xffff0000, v45
	s_mov_b32 s8, 0x3c0000
	v_pk_fma_f32 v[8:9], v[8:9], v[46:47], v[48:49] op_sel_hi:[1,0,1]
	v_add_co_u32_e32 v46, vcc, s8, v10
	v_cvt_pk_bf16_f32 v45, v8, v9
	s_nop 0
	v_addc_co_u32_e32 v47, vcc, 0, v11, vcc
	global_store_dword v[46:47], v45, off
	v_lshlrev_b32_e32 v46, 16, v41
	v_and_b32_e32 v47, 0xffff0000, v41
	s_mov_b32 s8, 0x400000
	v_pk_fma_f32 v[8:9], v[8:9], v[44:45], v[46:47] op_sel_hi:[1,0,1]
	v_add_co_u32_e32 v44, vcc, s8, v10
	v_cvt_pk_bf16_f32 v41, v8, v9
	s_nop 0
	v_addc_co_u32_e32 v45, vcc, 0, v11, vcc
	global_store_dword v[44:45], v41, off
	v_lshlrev_b32_e32 v44, 16, v39
	v_and_b32_e32 v45, 0xffff0000, v39
	s_mov_b32 s8, 0x440000
	v_pk_fma_f32 v[8:9], v[8:9], v[42:43], v[44:45] op_sel_hi:[1,0,1]
	v_add_co_u32_e32 v44, vcc, s8, v10
	v_cvt_pk_bf16_f32 v39, v8, v9
	s_nop 0
	v_addc_co_u32_e32 v45, vcc, 0, v11, vcc
	global_store_dword v[44:45], v39, off
	v_lshlrev_b32_e32 v44, 16, v37
	v_and_b32_e32 v45, 0xffff0000, v37
	s_mov_b32 s8, 0x480000
	v_pk_fma_f32 v[8:9], v[8:9], v[40:41], v[44:45] op_sel_hi:[1,0,1]
	v_add_co_u32_e32 v40, vcc, s8, v10
	v_cvt_pk_bf16_f32 v37, v8, v9
	s_nop 0
	v_addc_co_u32_e32 v41, vcc, 0, v11, vcc
	global_store_dword v[40:41], v37, off
	v_lshlrev_b32_e32 v40, 16, v35
	v_and_b32_e32 v41, 0xffff0000, v35
	s_mov_b32 s8, 0x4c0000
	v_pk_fma_f32 v[8:9], v[8:9], v[38:39], v[40:41] op_sel_hi:[1,0,1]
	v_add_co_u32_e32 v38, vcc, s8, v10
	v_cvt_pk_bf16_f32 v35, v8, v9
	s_nop 0
	v_addc_co_u32_e32 v39, vcc, 0, v11, vcc
	global_store_dword v[38:39], v35, off
	v_lshlrev_b32_e32 v38, 16, v29
	v_and_b32_e32 v39, 0xffff0000, v29
	s_mov_b32 s8, 0x500000
	v_pk_fma_f32 v[8:9], v[8:9], v[36:37], v[38:39] op_sel_hi:[1,0,1]
	v_add_co_u32_e32 v36, vcc, s8, v10
	v_cvt_pk_bf16_f32 v29, v8, v9
	s_nop 0
	v_addc_co_u32_e32 v37, vcc, 0, v11, vcc
	global_store_dword v[36:37], v29, off
	v_lshlrev_b32_e32 v36, 16, v19
	v_and_b32_e32 v37, 0xffff0000, v19
	s_mov_b32 s8, 0x540000
	v_pk_fma_f32 v[44:45], v[8:9], v[34:35], v[36:37] op_sel_hi:[1,0,1]
	v_add_co_u32_e32 v8, vcc, s8, v10
	s_mov_b32 s8, 0x580000
	s_nop 0
	v_addc_co_u32_e32 v9, vcc, 0, v11, vcc
	v_cvt_pk_bf16_f32 v19, v44, v45
	v_lshlrev_b32_e32 v46, 16, v5
	v_and_b32_e32 v47, 0xffff0000, v5
	v_add_co_u32_e32 v42, vcc, s8, v10
	global_store_dword v[8:9], v19, off
	v_lshlrev_b32_e32 v48, 16, v13
	v_and_b32_e32 v49, 0xffff0000, v13
	v_lshlrev_b32_e32 v34, 16, v33
	v_and_b32_e32 v35, 0xffff0000, v33
	v_lshlrev_b32_e32 v8, 16, v43
	v_and_b32_e32 v9, 0xffff0000, v43
	v_pk_fma_f32 v[32:33], v[44:45], v[32:33], v[46:47] op_sel_hi:[1,0,1]
	v_addc_co_u32_e32 v43, vcc, 0, v11, vcc
	s_mov_b32 s8, 0x5c0000
	v_lshlrev_b32_e32 v36, 16, v31
	v_and_b32_e32 v37, 0xffff0000, v31
	v_cvt_pk_bf16_f32 v5, v32, v33
	v_pk_fma_f32 v[30:31], v[32:33], v[30:31], v[48:49] op_sel_hi:[1,0,1]
	v_add_co_u32_e32 v32, vcc, s8, v10
	v_lshlrev_b32_e32 v50, 16, v15
	v_and_b32_e32 v51, 0xffff0000, v15
	v_addc_co_u32_e32 v33, vcc, 0, v11, vcc
	s_mov_b32 s8, 0x600000
	global_store_dword v[42:43], v5, off
	v_cvt_pk_bf16_f32 v5, v30, v31
	v_pk_fma_f32 v[28:29], v[30:31], v[28:29], v[50:51] op_sel_hi:[1,0,1]
	v_add_co_u32_e32 v30, vcc, s8, v10
	v_lshlrev_b32_e32 v52, 16, v17
	v_and_b32_e32 v53, 0xffff0000, v17
	v_addc_co_u32_e32 v31, vcc, 0, v11, vcc
	s_mov_b32 s8, 0x640000
	v_lshlrev_b32_e32 v38, 16, v27
	v_and_b32_e32 v39, 0xffff0000, v27
	global_store_dword v[32:33], v5, off
	v_cvt_pk_bf16_f32 v5, v28, v29
	v_pk_fma_f32 v[26:27], v[28:29], v[26:27], v[52:53] op_sel_hi:[1,0,1]
	v_add_co_u32_e32 v28, vcc, s8, v10
	v_lshlrev_b32_e32 v54, 16, v21
	v_and_b32_e32 v55, 0xffff0000, v21
	v_addc_co_u32_e32 v29, vcc, 0, v11, vcc
	s_mov_b32 s8, 0x680000
	v_lshlrev_b32_e32 v40, 16, v25
	v_and_b32_e32 v41, 0xffff0000, v25
	global_store_dword v[30:31], v5, off
	v_cvt_pk_bf16_f32 v5, v26, v27
	v_pk_fma_f32 v[24:25], v[26:27], v[24:25], v[54:55] op_sel_hi:[1,0,1]
	v_add_co_u32_e32 v26, vcc, s8, v10
	v_lshlrev_b32_e32 v56, 16, v23
	v_and_b32_e32 v57, 0xffff0000, v23
	v_addc_co_u32_e32 v27, vcc, 0, v11, vcc
	s_mov_b32 s8, 0x6c0000
	global_store_dword v[28:29], v5, off
	v_cvt_pk_bf16_f32 v5, v24, v25
	v_pk_fma_f32 v[22:23], v[24:25], v[22:23], v[56:57] op_sel_hi:[1,0,1]
	v_add_co_u32_e32 v24, vcc, s8, v10
	s_mov_b32 s8, 0x700000
	s_nop 0
	v_addc_co_u32_e32 v25, vcc, 0, v11, vcc
	global_store_dword v[26:27], v5, off
	v_cvt_pk_bf16_f32 v5, v22, v23
	v_pk_fma_f32 v[20:21], v[22:23], v[20:21], v[40:41] op_sel_hi:[1,0,1]
	v_add_co_u32_e32 v22, vcc, s8, v10
	s_mov_b32 s8, 0x740000
	s_nop 0
	v_addc_co_u32_e32 v23, vcc, 0, v11, vcc
	global_store_dword v[24:25], v5, off
	v_cvt_pk_bf16_f32 v5, v20, v21
	v_pk_fma_f32 v[18:19], v[20:21], v[18:19], v[38:39] op_sel_hi:[1,0,1]
	v_add_co_u32_e32 v20, vcc, s8, v10
	s_mov_b32 s8, 0x780000
	s_nop 0
	v_addc_co_u32_e32 v21, vcc, 0, v11, vcc
	global_store_dword v[22:23], v5, off
	v_cvt_pk_bf16_f32 v5, v18, v19
	v_pk_fma_f32 v[16:17], v[18:19], v[16:17], v[36:37] op_sel_hi:[1,0,1]
	v_add_co_u32_e32 v18, vcc, s8, v10
	global_store_dword v[20:21], v5, off
	s_nop 0
	v_addc_co_u32_e32 v19, vcc, 0, v11, vcc
	v_add_co_u32_e32 v10, vcc, 0x7c0000, v10
	v_cvt_pk_bf16_f32 v5, v16, v17
	v_pk_fma_f32 v[14:15], v[16:17], v[14:15], v[34:35] op_sel_hi:[1,0,1]
	v_addc_co_u32_e32 v11, vcc, 0, v11, vcc
	global_store_dword v[18:19], v5, off
	v_cvt_pk_bf16_f32 v5, v14, v15
	s_waitcnt vmcnt(30)
	v_pk_fma_f32 v[8:9], v[14:15], v[12:13], v[8:9] op_sel_hi:[1,0,1]
	s_mov_b32 s12, 32
	s_and_b64 vcc, exec, s[4:5]
	s_mov_b64 s[4:5], 0
	global_store_dword v[10:11], v5, off
	s_cbranch_vccnz .LBB0_670
	s_lshl_b32 s4, s22, 4
	s_add_i32 s4, s4, s11
	s_or_b32 s4, s4, s17
	s_ashr_i32 s5, s4, 31
	s_lshl_b64 s[4:5], s[4:5], 15
	v_ashrrev_i32_e32 v5, 31, v4
	s_add_u32 s4, s2, s4
	s_addc_u32 s5, s3, s5
	v_lshlrev_b64 v[4:5], 9, v[4:5]
	v_lshl_add_u64 v[4:5], s[4:5], 0, v[4:5]
	v_lshlrev_b32_e32 v6, 2, v0
	v_mov_b32_e32 v7, v3
	s_add_i32 s16, s16, 1
	v_lshl_add_u64 v[4:5], v[4:5], 0, v[6:7]
	s_cmp_eq_u32 s16, s6
	global_store_dwordx2 v[4:5], v[8:9], off
	s_cbranch_scc0 .LBB0_669
